# grid barrier leader path: unused XGEN bump removed and the acquire invalidate issued without first draining the leader's own release atomic (on top of opt15)
# baseline (speedup 1.0000x reference)
; __device__ __forceinline__ unsigned xb_add(unsigned* p, unsigned v) { return __hip_atomic_fetch_add(p, v, __ATOMIC_RELAXED, __HIP_MEMORY_SCOPE_AGENT); }
; __device__ __forceinline__ void xcd_barrier(const XcdBarrier& b) {
;     ...
;             __builtin_amdgcn_fence(__ATOMIC_ACQUIRE, "agent");
;             xb_add(&bar[XB_XGEN(b.x)], 1u);
;             asm volatile("s_waitcnt vmcnt(0)" ::: "memory");
.LBB0_564:
	s_or_b64 exec, exec, s[6:7]
	s_mov_b64 s[6:7], exec
	v_mbcnt_lo_u32_b32 v0, s6, 0
	v_mbcnt_hi_u32_b32 v0, s7, v0
	v_cmp_eq_u32_e32 vcc, 0, v0
	buffer_inv sc1
	s_and_saveexec_b64 s[10:11], vcc
	s_cbranch_execz .LBB0_566
	s_bcnt1_i32_b64 s2, s[6:7]
	v_mov_b32_e32 v0, s2
